# P3 e1: the four window-before sums batched (all loads of a window in flight, one wait) instead of one dependent load per trip
# speedup vs baseline: 1.0033x; 1.0033x over previous
.LBB0_659:
	s_or_b64 exec, exec, s[20:21]
	s_add_i32 s16, s3, 7
	s_ashr_i32 s17, s16, 31
	s_lshr_b32 s17, s17, 29
	s_add_i32 s16, s16, s17
	s_ashr_i32 s17, s16, 3
	s_mul_i32 s18, s3, s2
	s_mul_i32 s16, s17, s33
	s_add_i32 s16, s16, s18
	s_add_i32 s3, s18, s3
	s_add_i32 s17, s16, s17
	v_mov_b32_e32 v0, s3
	v_mov_b32_e32 v1, 0x3000
	v_min3_i32 v0, s17, v0, v1
	v_cmp_ge_i32_e32 vcc, s16, v0
	v_readfirstlane_b32 s3, v0
	v_mov_b32_e32 v0, v58
	s_cbranch_vccnz .LBB0_683
	s_add_u32 s20, s10, 0x36fd8000
	s_addc_u32 s21, s11, 0
	s_ashr_i32 s17, s16, 31
	s_mul_i32 s18, s16, 0xc00
	s_mul_hi_i32 s19, s16, 0xc00
	s_add_u32 s24, s20, s18
	s_addc_u32 s25, s21, s19
	s_cmpk_lt_i32 s16, 0x1000
	s_movk_i32 s22, 0xff
	s_cselect_b32 s22, s22, 0x3ff
	s_movk_i32 s23, 0x100
	s_cselect_b32 s27, s23, 0x400
	s_and_b32 s26, s22, s16
	s_sub_i32 s31, s16, s26
	s_lshl_b64 s[22:23], s[16:17], 10
	s_add_u32 s34, s10, s22
	s_addc_u32 s35, s11, s23
	s_add_i32 s17, s26, 1
	s_add_i32 s48, s31, -1
	s_min_u32 s17, s17, s27
	s_add_i32 s28, s48, s17
	s_mul_hi_i32 s29, s28, 0xc00
	s_mulk_i32 s28, 0xc00
	v_sub_u32_e64 v46, s26, 2 clamp
	s_add_u32 s36, s20, s28
	v_readfirstlane_b32 s28, v46
	s_addc_u32 s37, s21, s29
	s_add_i32 s28, s28, s31
	s_mul_hi_i32 s29, s28, 0xc00
	s_mulk_i32 s28, 0xc00
	s_add_u32 s38, s20, s28
	s_addc_u32 s39, s21, s29
	s_add_i32 s28, s26, 2
	s_min_u32 s29, s28, s27
	s_add_i32 s29, s48, s29
	s_mul_hi_i32 s30, s29, 0xc00
	s_mulk_i32 s29, 0xc00
	v_sub_u32_e64 v47, s26, 3 clamp
	s_add_u32 s40, s20, s29
	v_readfirstlane_b32 s29, v47
	s_addc_u32 s41, s21, s30
	s_add_i32 s29, s29, s31
	s_mul_hi_i32 s30, s29, 0xc00
	s_mulk_i32 s29, 0xc00
	s_add_u32 s42, s20, s29
	s_addc_u32 s43, s21, s30
	s_add_i32 s29, s26, 4
	s_min_u32 s30, s29, s27
	s_add_i32 s30, s48, s30
	s_mul_hi_i32 s45, s30, 0xc00
	s_mulk_i32 s30, 0xc00
	v_sub_u32_e64 v59, s26, 5 clamp
	s_add_u32 s44, s20, s30
	v_readfirstlane_b32 s30, v59
	s_addc_u32 s45, s21, s45
	s_add_i32 s30, s30, s31
	s_mul_hi_i32 s47, s30, 0xc00
	s_mulk_i32 s30, 0xc00
	s_add_u32 s46, s20, s30
	s_addc_u32 s47, s21, s47
	s_add_i32 s30, s26, 8
	s_min_u32 s49, s30, s27
	v_lshlrev_b32_e32 v32, 2, v0
	s_add_i32 s48, s48, s49
	v_ashrrev_i32_e32 v33, 31, v32
	s_mul_hi_i32 s49, s48, 0xc00
	s_mulk_i32 s48, 0xc00
	v_sub_u32_e64 v60, s26, 9 clamp
	v_lshlrev_b64 v[48:49], 2, v[32:33]
	s_add_u32 s48, s20, s48
	v_readfirstlane_b32 s50, v60
	s_waitcnt lgkmcnt(0)
	v_lshl_add_u64 v[4:5], s[12:13], 0, v[48:49]
	v_lshl_add_u64 v[12:13], s[34:35], 0, v[48:49]
	s_mov_b32 s12, 0x363d8000
	s_addc_u32 s49, s21, s49
	s_add_i32 s31, s50, s31
	v_lshlrev_b64 v[50:51], 1, v[32:33]
	v_add_co_u32_e32 v12, vcc, s12, v12
	s_mul_hi_i32 s51, s31, 0xc00
	s_mulk_i32 s31, 0xc00
	v_lshl_add_u64 v[8:9], s[14:15], 0, v[48:49]
	v_addc_co_u32_e32 v13, vcc, 0, v13, vcc
	v_lshl_add_u64 v[18:19], s[36:37], 0, v[50:51]
	s_add_u32 s50, s20, s31
	global_load_dwordx4 v[0:3], v[4:5], off
	s_nop 0
	global_load_dwordx4 v[4:7], v[4:5], off offset:1024
	v_lshl_add_u64 v[16:17], s[24:25], 0, v[50:51]
	global_load_dwordx4 v[8:11], v[8:9], off
	s_nop 0
	global_load_dwordx4 v[12:15], v[12:13], off
	s_nop 0
	global_load_dwordx2 v[30:31], v[18:19], off offset:1024
	v_lshl_add_u64 v[18:19], s[38:39], 0, v[50:51]
	s_addc_u32 s51, s21, s51
	global_load_dwordx2 v[40:41], v[16:17], off
	global_load_dwordx2 v[38:39], v[16:17], off offset:512
	global_load_dwordx2 v[36:37], v[16:17], off offset:1024
	global_load_dwordx2 v[34:35], v[16:17], off offset:1536
	v_lshl_add_u64 v[20:21], s[40:41], 0, v[50:51]
	v_lshl_add_u64 v[42:43], s[42:43], 0, v[50:51]
	v_lshl_add_u64 v[44:45], s[44:45], 0, v[50:51]
	global_load_dwordx2 v[28:29], v[18:19], off offset:1024
	global_load_dwordx2 v[26:27], v[20:21], off offset:1536
	global_load_dwordx2 v[24:25], v[42:43], off offset:1536
	global_load_dwordx2 v[22:23], v[44:45], off offset:2048
	v_lshl_add_u64 v[52:53], s[46:47], 0, v[50:51]
	global_load_dwordx2 v[44:45], v[16:17], off offset:2048
	global_load_dwordx2 v[42:43], v[16:17], off offset:2560
	v_lshl_add_u64 v[54:55], s[48:49], 0, v[50:51]
	v_lshl_add_u64 v[56:57], s[50:51], 0, v[50:51]
	global_load_dwordx2 v[20:21], v[52:53], off offset:2048
	global_load_dwordx2 v[18:19], v[54:55], off offset:2560
	global_load_dwordx2 v[16:17], v[56:57], off offset:2560
	s_min_u32 s15, s26, s27
	v_add_u32_e32 v52, 0x200, v32
	v_cmp_le_u32_e32 vcc, s15, v46
	v_ashrrev_i32_e32 v53, 31, v52
	v_mov_b32_e32 v89, 0
	v_readfirstlane_b32 s14, v47
	v_readfirstlane_b32 s13, v59
	v_readfirstlane_b32 s12, v60
	s_and_b64 vcc, exec, vcc
	v_lshl_add_u64 v[84:85], v[52:53], 1, s[20:21]
	v_mov_b32_e32 v88, v89
	v_mov_b32_e32 v87, v89
	v_mov_b32_e32 v86, v89
	s_cbranch_vccnz .LBB0_663
	s_min_u32 s24, s26, 2
	v_mov_b32_e32 v86, 0
	s_sub_i32 s24, s16, s24
	v_mov_b32_e32 v33, 0xc00
	v_mov_b32_e32 v87, v86
	v_mov_b32_e32 v88, v86
	v_mov_b32_e32 v89, v86
	v_readfirstlane_b32 s98, v46
	s_nop 3
	s_mov_b32 s99, s24
	v_mad_i64_i32 v[206:207], s[34:35], s99, v33, v[84:85]
	global_load_dwordx2 v[206:207], v[206:207], off
	s_add_i32 s98, s98, 1
	s_add_i32 s99, s99, 1
	s_cmp_lt_u32 s98, s15
	s_cbranch_scc0 .Lmy_e1w1
	v_mad_i64_i32 v[208:209], s[34:35], s99, v33, v[84:85]
	global_load_dwordx2 v[208:209], v[208:209], off
.Lmy_e1w1:
	s_waitcnt vmcnt(0)
	v_lshlrev_b32_e32 v54, 16, v206
	v_and_b32_e32 v55, 0xffff0000, v206
	v_lshlrev_b32_e32 v52, 16, v207
	v_and_b32_e32 v53, 0xffff0000, v207
	v_pk_add_f32 v[88:89], v[88:89], v[52:53]
	v_pk_add_f32 v[86:87], v[86:87], v[54:55]
	v_add_u32_e32 v46, 1, v46
	v_cmp_le_u32_e32 vcc, s15, v46
	s_add_i32 s24, s24, 1
	s_and_b64 vcc, exec, vcc
	s_cbranch_vccnz .Lmy_e1x1
	v_lshlrev_b32_e32 v54, 16, v208
	v_and_b32_e32 v55, 0xffff0000, v208
	v_lshlrev_b32_e32 v52, 16, v209
	v_and_b32_e32 v53, 0xffff0000, v209
	v_pk_add_f32 v[88:89], v[88:89], v[52:53]
	v_pk_add_f32 v[86:87], v[86:87], v[54:55]
	v_add_u32_e32 v46, 1, v46
	v_cmp_le_u32_e32 vcc, s15, v46
	s_add_i32 s24, s24, 1
	s_and_b64 vcc, exec, vcc
	s_cbranch_vccz .LBB0_662
	s_branch .Lmy_e1x1

.Lmy_e1x1:
.LBB0_663:
	v_add_u32_e32 v52, 0x300, v32
	s_waitcnt vmcnt(0)
	v_lshlrev_b32_e32 v98, 16, v40
	v_and_b32_e32 v99, 0xffff0000, v40
	v_lshlrev_b32_e32 v100, 16, v41
	v_and_b32_e32 v101, 0xffff0000, v41
	v_lshlrev_b32_e32 v94, 16, v38
	v_and_b32_e32 v95, 0xffff0000, v38
	v_lshlrev_b32_e32 v96, 16, v39
	v_and_b32_e32 v97, 0xffff0000, v39
	v_lshlrev_b32_e32 v149, 16, v36
	v_and_b32_e32 v150, 0xffff0000, v36
	v_lshlrev_b32_e32 v147, 16, v37
	v_and_b32_e32 v148, 0xffff0000, v37
	v_lshlrev_b32_e32 v145, 16, v34
	v_and_b32_e32 v146, 0xffff0000, v34
	v_lshlrev_b32_e32 v143, 16, v35
	v_and_b32_e32 v144, 0xffff0000, v35
	v_lshlrev_b32_e32 v141, 16, v44
	v_and_b32_e32 v142, 0xffff0000, v44
	v_lshlrev_b32_e32 v139, 16, v45
	v_and_b32_e32 v140, 0xffff0000, v45
	v_lshlrev_b32_e32 v137, 16, v42
	v_and_b32_e32 v138, 0xffff0000, v42
	v_lshlrev_b32_e32 v135, 16, v43
	v_and_b32_e32 v136, 0xffff0000, v43
	s_cmp_ge_u32 s14, s17
	v_ashrrev_i32_e32 v53, 31, v52
	s_cbranch_scc1 .LBB0_666
	s_min_u32 s15, s26, 3
	v_mov_b32_e32 v90, 0
	v_lshl_add_u64 v[34:35], v[52:53], 1, s[20:21]
	s_sub_i32 s15, s16, s15
	v_mov_b32_e32 v33, 0xc00
	v_mov_b32_e32 v91, v90
	v_mov_b32_e32 v92, v90
	v_mov_b32_e32 v93, v90
	s_mov_b32 s98, s14
	s_mov_b32 s99, s15
	v_mad_i64_i32 v[206:207], s[24:25], s99, v33, v[34:35]
	global_load_dwordx2 v[206:207], v[206:207], off
	s_add_i32 s98, s98, 1
	s_add_i32 s99, s99, 1
	s_cmp_lt_u32 s98, s17
	s_cbranch_scc0 .Lmy_e1w2
	v_mad_i64_i32 v[208:209], s[24:25], s99, v33, v[34:35]
	global_load_dwordx2 v[208:209], v[208:209], off
	s_add_i32 s98, s98, 1
	s_add_i32 s99, s99, 1
	s_cmp_lt_u32 s98, s17
	s_cbranch_scc0 .Lmy_e1w2
	v_mad_i64_i32 v[210:211], s[24:25], s99, v33, v[34:35]
	global_load_dwordx2 v[210:211], v[210:211], off
	s_add_i32 s98, s98, 1
	s_add_i32 s99, s99, 1
	s_cmp_lt_u32 s98, s17
	s_cbranch_scc0 .Lmy_e1w2
	v_mad_i64_i32 v[212:213], s[24:25], s99, v33, v[34:35]
	global_load_dwordx2 v[212:213], v[212:213], off
.Lmy_e1w2:
	s_waitcnt vmcnt(0)
	v_lshlrev_b32_e32 v38, 16, v206
	v_and_b32_e32 v39, 0xffff0000, v206
	v_lshlrev_b32_e32 v36, 16, v207
	v_and_b32_e32 v37, 0xffff0000, v207
	v_pk_add_f32 v[92:93], v[92:93], v[36:37]
	v_pk_add_f32 v[90:91], v[90:91], v[38:39]
	s_add_i32 s14, s14, 1
	s_add_i32 s15, s15, 1
	s_cmp_lt_u32 s14, s17
	s_cbranch_scc0 .Lmy_e1x2
	v_lshlrev_b32_e32 v38, 16, v208
	v_and_b32_e32 v39, 0xffff0000, v208
	v_lshlrev_b32_e32 v36, 16, v209
	v_and_b32_e32 v37, 0xffff0000, v209
	v_pk_add_f32 v[92:93], v[92:93], v[36:37]
	v_pk_add_f32 v[90:91], v[90:91], v[38:39]
	s_add_i32 s14, s14, 1
	s_add_i32 s15, s15, 1
	s_cmp_lt_u32 s14, s17
	s_cbranch_scc0 .Lmy_e1x2
	v_lshlrev_b32_e32 v38, 16, v210
	v_and_b32_e32 v39, 0xffff0000, v210
	v_lshlrev_b32_e32 v36, 16, v211
	v_and_b32_e32 v37, 0xffff0000, v211
	v_pk_add_f32 v[92:93], v[92:93], v[36:37]
	v_pk_add_f32 v[90:91], v[90:91], v[38:39]
	s_add_i32 s14, s14, 1
	s_add_i32 s15, s15, 1
	s_cmp_lt_u32 s14, s17
	s_cbranch_scc0 .Lmy_e1x2
	v_lshlrev_b32_e32 v38, 16, v212
	v_and_b32_e32 v39, 0xffff0000, v212
	v_lshlrev_b32_e32 v36, 16, v213
	v_and_b32_e32 v37, 0xffff0000, v213
	v_pk_add_f32 v[92:93], v[92:93], v[36:37]
	v_pk_add_f32 v[90:91], v[90:91], v[38:39]
	s_add_i32 s14, s14, 1
	s_add_i32 s15, s15, 1
	s_cmp_lt_u32 s14, s17
	s_cbranch_scc1 .LBB0_665
	s_branch .Lmy_e1x2
.LBB0_665:
	v_mad_i64_i32 v[36:37], s[24:25], s15, v33, v[34:35]
	global_load_dwordx2 v[36:37], v[36:37], off
	s_add_i32 s14, s14, 1
	s_add_i32 s15, s15, 1
	s_cmp_lt_u32 s14, s17
	s_waitcnt vmcnt(0)
	v_lshlrev_b32_e32 v38, 16, v36
	v_and_b32_e32 v39, 0xffff0000, v36
	v_lshlrev_b32_e32 v36, 16, v37
	v_and_b32_e32 v37, 0xffff0000, v37
	v_pk_add_f32 v[92:93], v[92:93], v[36:37]
	v_pk_add_f32 v[90:91], v[90:91], v[38:39]
	s_cbranch_scc1 .LBB0_665
.Lmy_e1x2:
	s_branch .LBB0_667
.LBB0_666:
	v_mov_b32_e32 v90, 0
	v_mov_b32_e32 v91, v90
	v_mov_b32_e32 v92, v90
	v_mov_b32_e32 v93, v90
.LBB0_667:
	s_add_i32 s14, s26, 3
	v_add_u32_e32 v54, 0x400, v32
	s_min_u32 s14, s14, s27
	s_cmp_ge_u32 s13, s14
	v_ashrrev_i32_e32 v55, 31, v54
	s_cbranch_scc1 .LBB0_670
	s_min_u32 s15, s26, 5
	v_mov_b32_e32 v102, 0
	v_lshl_add_u64 v[34:35], v[54:55], 1, s[20:21]
	s_sub_i32 s15, s16, s15
	v_mov_b32_e32 v33, 0xc00
	v_mov_b32_e32 v103, v102
	v_mov_b32_e32 v104, v102
	v_mov_b32_e32 v105, v102
	s_mov_b32 s98, s13
	s_mov_b32 s99, s15
	v_mad_i64_i32 v[206:207], s[24:25], s99, v33, v[34:35]
	global_load_dwordx2 v[206:207], v[206:207], off
	s_add_i32 s98, s98, 1
	s_add_i32 s99, s99, 1
	s_cmp_lt_u32 s98, s14
	s_cbranch_scc0 .Lmy_e1w3
	v_mad_i64_i32 v[208:209], s[24:25], s99, v33, v[34:35]
	global_load_dwordx2 v[208:209], v[208:209], off
	s_add_i32 s98, s98, 1
	s_add_i32 s99, s99, 1
	s_cmp_lt_u32 s98, s14
	s_cbranch_scc0 .Lmy_e1w3
	v_mad_i64_i32 v[210:211], s[24:25], s99, v33, v[34:35]
	global_load_dwordx2 v[210:211], v[210:211], off
	s_add_i32 s98, s98, 1
	s_add_i32 s99, s99, 1
	s_cmp_lt_u32 s98, s14
	s_cbranch_scc0 .Lmy_e1w3
	v_mad_i64_i32 v[212:213], s[24:25], s99, v33, v[34:35]
	global_load_dwordx2 v[212:213], v[212:213], off
	s_add_i32 s98, s98, 1
	s_add_i32 s99, s99, 1
	s_cmp_lt_u32 s98, s14
	s_cbranch_scc0 .Lmy_e1w3
	v_mad_i64_i32 v[214:215], s[24:25], s99, v33, v[34:35]
	global_load_dwordx2 v[214:215], v[214:215], off
	s_add_i32 s98, s98, 1
	s_add_i32 s99, s99, 1
	s_cmp_lt_u32 s98, s14
	s_cbranch_scc0 .Lmy_e1w3
	v_mad_i64_i32 v[216:217], s[24:25], s99, v33, v[34:35]
	global_load_dwordx2 v[216:217], v[216:217], off
	s_add_i32 s98, s98, 1
	s_add_i32 s99, s99, 1
	s_cmp_lt_u32 s98, s14
	s_cbranch_scc0 .Lmy_e1w3
	v_mad_i64_i32 v[218:219], s[24:25], s99, v33, v[34:35]
	global_load_dwordx2 v[218:219], v[218:219], off
	s_add_i32 s98, s98, 1
	s_add_i32 s99, s99, 1
	s_cmp_lt_u32 s98, s14
	s_cbranch_scc0 .Lmy_e1w3
	v_mad_i64_i32 v[220:221], s[24:25], s99, v33, v[34:35]
	global_load_dwordx2 v[220:221], v[220:221], off
.Lmy_e1w3:
	s_waitcnt vmcnt(0)
	v_lshlrev_b32_e32 v38, 16, v206
	v_and_b32_e32 v39, 0xffff0000, v206
	v_lshlrev_b32_e32 v36, 16, v207
	v_and_b32_e32 v37, 0xffff0000, v207
	v_pk_add_f32 v[104:105], v[104:105], v[36:37]
	v_pk_add_f32 v[102:103], v[102:103], v[38:39]
	s_add_i32 s13, s13, 1
	s_add_i32 s15, s15, 1
	s_cmp_lt_u32 s13, s14
	s_cbranch_scc0 .Lmy_e1x3
	v_lshlrev_b32_e32 v38, 16, v208
	v_and_b32_e32 v39, 0xffff0000, v208
	v_lshlrev_b32_e32 v36, 16, v209
	v_and_b32_e32 v37, 0xffff0000, v209
	v_pk_add_f32 v[104:105], v[104:105], v[36:37]
	v_pk_add_f32 v[102:103], v[102:103], v[38:39]
	s_add_i32 s13, s13, 1
	s_add_i32 s15, s15, 1
	s_cmp_lt_u32 s13, s14
	s_cbranch_scc0 .Lmy_e1x3
	v_lshlrev_b32_e32 v38, 16, v210
	v_and_b32_e32 v39, 0xffff0000, v210
	v_lshlrev_b32_e32 v36, 16, v211
	v_and_b32_e32 v37, 0xffff0000, v211
	v_pk_add_f32 v[104:105], v[104:105], v[36:37]
	v_pk_add_f32 v[102:103], v[102:103], v[38:39]
	s_add_i32 s13, s13, 1
	s_add_i32 s15, s15, 1
	s_cmp_lt_u32 s13, s14
	s_cbranch_scc0 .Lmy_e1x3
	v_lshlrev_b32_e32 v38, 16, v212
	v_and_b32_e32 v39, 0xffff0000, v212
	v_lshlrev_b32_e32 v36, 16, v213
	v_and_b32_e32 v37, 0xffff0000, v213
	v_pk_add_f32 v[104:105], v[104:105], v[36:37]
	v_pk_add_f32 v[102:103], v[102:103], v[38:39]
	s_add_i32 s13, s13, 1
	s_add_i32 s15, s15, 1
	s_cmp_lt_u32 s13, s14
	s_cbranch_scc0 .Lmy_e1x3
	v_lshlrev_b32_e32 v38, 16, v214
	v_and_b32_e32 v39, 0xffff0000, v214
	v_lshlrev_b32_e32 v36, 16, v215
	v_and_b32_e32 v37, 0xffff0000, v215
	v_pk_add_f32 v[104:105], v[104:105], v[36:37]
	v_pk_add_f32 v[102:103], v[102:103], v[38:39]
	s_add_i32 s13, s13, 1
	s_add_i32 s15, s15, 1
	s_cmp_lt_u32 s13, s14
	s_cbranch_scc0 .Lmy_e1x3
	v_lshlrev_b32_e32 v38, 16, v216
	v_and_b32_e32 v39, 0xffff0000, v216
	v_lshlrev_b32_e32 v36, 16, v217
	v_and_b32_e32 v37, 0xffff0000, v217
	v_pk_add_f32 v[104:105], v[104:105], v[36:37]
	v_pk_add_f32 v[102:103], v[102:103], v[38:39]
	s_add_i32 s13, s13, 1
	s_add_i32 s15, s15, 1
	s_cmp_lt_u32 s13, s14
	s_cbranch_scc0 .Lmy_e1x3
	v_lshlrev_b32_e32 v38, 16, v218
	v_and_b32_e32 v39, 0xffff0000, v218
	v_lshlrev_b32_e32 v36, 16, v219
	v_and_b32_e32 v37, 0xffff0000, v219
	v_pk_add_f32 v[104:105], v[104:105], v[36:37]
	v_pk_add_f32 v[102:103], v[102:103], v[38:39]
	s_add_i32 s13, s13, 1
	s_add_i32 s15, s15, 1
	s_cmp_lt_u32 s13, s14
	s_cbranch_scc0 .Lmy_e1x3
	v_lshlrev_b32_e32 v38, 16, v220
	v_and_b32_e32 v39, 0xffff0000, v220
	v_lshlrev_b32_e32 v36, 16, v221
	v_and_b32_e32 v37, 0xffff0000, v221
	v_pk_add_f32 v[104:105], v[104:105], v[36:37]
	v_pk_add_f32 v[102:103], v[102:103], v[38:39]
	s_add_i32 s13, s13, 1
	s_add_i32 s15, s15, 1
	s_cmp_lt_u32 s13, s14
	s_cbranch_scc1 .LBB0_669
	s_branch .Lmy_e1x3
.LBB0_669:
	v_mad_i64_i32 v[36:37], s[24:25], s15, v33, v[34:35]
	global_load_dwordx2 v[36:37], v[36:37], off
	s_add_i32 s13, s13, 1
	s_add_i32 s15, s15, 1
	s_cmp_lt_u32 s13, s14
	s_waitcnt vmcnt(0)
	v_lshlrev_b32_e32 v38, 16, v36
	v_and_b32_e32 v39, 0xffff0000, v36
	v_lshlrev_b32_e32 v36, 16, v37
	v_and_b32_e32 v37, 0xffff0000, v37
	v_pk_add_f32 v[104:105], v[104:105], v[36:37]
	v_pk_add_f32 v[102:103], v[102:103], v[38:39]
	s_cbranch_scc1 .LBB0_669
.Lmy_e1x3:
	s_branch .LBB0_671
.LBB0_670:
	v_mov_b32_e32 v102, 0
	v_mov_b32_e32 v103, v102
	v_mov_b32_e32 v104, v102
	v_mov_b32_e32 v105, v102
.LBB0_671:
	s_add_i32 s13, s26, 7
	v_add_u32_e32 v56, 0x500, v32
	s_min_u32 s13, s13, s27
	s_cmp_ge_u32 s12, s13
	v_ashrrev_i32_e32 v57, 31, v56
	s_cbranch_scc1 .LBB0_674
	s_min_u32 s14, s26, 9
	v_mov_b32_e32 v106, 0
	v_lshl_add_u64 v[32:33], v[56:57], 1, s[20:21]
	s_sub_i32 s14, s16, s14
	v_mov_b32_e32 v34, 0xc00
	v_mov_b32_e32 v107, v106
	v_mov_b32_e32 v108, v106
	v_mov_b32_e32 v109, v106
	s_mov_b32 s98, s12
	s_mov_b32 s99, s14
	v_mad_i64_i32 v[206:207], s[24:25], s99, v34, v[32:33]
	global_load_dwordx2 v[206:207], v[206:207], off
	s_add_i32 s98, s98, 1
	s_add_i32 s99, s99, 1
	s_cmp_lt_u32 s98, s13
	s_cbranch_scc0 .Lmy_e1w4
	v_mad_i64_i32 v[208:209], s[24:25], s99, v34, v[32:33]
	global_load_dwordx2 v[208:209], v[208:209], off
	s_add_i32 s98, s98, 1
	s_add_i32 s99, s99, 1
	s_cmp_lt_u32 s98, s13
	s_cbranch_scc0 .Lmy_e1w4
	v_mad_i64_i32 v[210:211], s[24:25], s99, v34, v[32:33]
	global_load_dwordx2 v[210:211], v[210:211], off
	s_add_i32 s98, s98, 1
	s_add_i32 s99, s99, 1
	s_cmp_lt_u32 s98, s13
	s_cbranch_scc0 .Lmy_e1w4
	v_mad_i64_i32 v[212:213], s[24:25], s99, v34, v[32:33]
	global_load_dwordx2 v[212:213], v[212:213], off
	s_add_i32 s98, s98, 1
	s_add_i32 s99, s99, 1
	s_cmp_lt_u32 s98, s13
	s_cbranch_scc0 .Lmy_e1w4
	v_mad_i64_i32 v[214:215], s[24:25], s99, v34, v[32:33]
	global_load_dwordx2 v[214:215], v[214:215], off
	s_add_i32 s98, s98, 1
	s_add_i32 s99, s99, 1
	s_cmp_lt_u32 s98, s13
	s_cbranch_scc0 .Lmy_e1w4
	v_mad_i64_i32 v[216:217], s[24:25], s99, v34, v[32:33]
	global_load_dwordx2 v[216:217], v[216:217], off
	s_add_i32 s98, s98, 1
	s_add_i32 s99, s99, 1
	s_cmp_lt_u32 s98, s13
	s_cbranch_scc0 .Lmy_e1w4
	v_mad_i64_i32 v[218:219], s[24:25], s99, v34, v[32:33]
	global_load_dwordx2 v[218:219], v[218:219], off
	s_add_i32 s98, s98, 1
	s_add_i32 s99, s99, 1
	s_cmp_lt_u32 s98, s13
	s_cbranch_scc0 .Lmy_e1w4
	v_mad_i64_i32 v[220:221], s[24:25], s99, v34, v[32:33]
	global_load_dwordx2 v[220:221], v[220:221], off
	s_add_i32 s98, s98, 1
	s_add_i32 s99, s99, 1
	s_cmp_lt_u32 s98, s13
	s_cbranch_scc0 .Lmy_e1w4
	v_mad_i64_i32 v[222:223], s[24:25], s99, v34, v[32:33]
	global_load_dwordx2 v[222:223], v[222:223], off
	s_add_i32 s98, s98, 1
	s_add_i32 s99, s99, 1
	s_cmp_lt_u32 s98, s13
	s_cbranch_scc0 .Lmy_e1w4
	v_mad_i64_i32 v[224:225], s[24:25], s99, v34, v[32:33]
	global_load_dwordx2 v[224:225], v[224:225], off
	s_add_i32 s98, s98, 1
	s_add_i32 s99, s99, 1
	s_cmp_lt_u32 s98, s13
	s_cbranch_scc0 .Lmy_e1w4
	v_mad_i64_i32 v[226:227], s[24:25], s99, v34, v[32:33]
	global_load_dwordx2 v[226:227], v[226:227], off
	s_add_i32 s98, s98, 1
	s_add_i32 s99, s99, 1
	s_cmp_lt_u32 s98, s13
	s_cbranch_scc0 .Lmy_e1w4
	v_mad_i64_i32 v[228:229], s[24:25], s99, v34, v[32:33]
	global_load_dwordx2 v[228:229], v[228:229], off
	s_add_i32 s98, s98, 1
	s_add_i32 s99, s99, 1
	s_cmp_lt_u32 s98, s13
	s_cbranch_scc0 .Lmy_e1w4
	v_mad_i64_i32 v[230:231], s[24:25], s99, v34, v[32:33]
	global_load_dwordx2 v[230:231], v[230:231], off
	s_add_i32 s98, s98, 1
	s_add_i32 s99, s99, 1
	s_cmp_lt_u32 s98, s13
	s_cbranch_scc0 .Lmy_e1w4
	v_mad_i64_i32 v[232:233], s[24:25], s99, v34, v[32:33]
	global_load_dwordx2 v[232:233], v[232:233], off
	s_add_i32 s98, s98, 1
	s_add_i32 s99, s99, 1
	s_cmp_lt_u32 s98, s13
	s_cbranch_scc0 .Lmy_e1w4
	v_mad_i64_i32 v[234:235], s[24:25], s99, v34, v[32:33]
	global_load_dwordx2 v[234:235], v[234:235], off
	s_add_i32 s98, s98, 1
	s_add_i32 s99, s99, 1
	s_cmp_lt_u32 s98, s13
	s_cbranch_scc0 .Lmy_e1w4
	v_mad_i64_i32 v[236:237], s[24:25], s99, v34, v[32:33]
	global_load_dwordx2 v[236:237], v[236:237], off
.Lmy_e1w4:
	s_waitcnt vmcnt(0)
	v_lshlrev_b32_e32 v38, 16, v206
	v_and_b32_e32 v39, 0xffff0000, v206
	v_lshlrev_b32_e32 v36, 16, v207
	v_and_b32_e32 v37, 0xffff0000, v207
	v_pk_add_f32 v[108:109], v[108:109], v[36:37]
	v_pk_add_f32 v[106:107], v[106:107], v[38:39]
	s_add_i32 s12, s12, 1
	s_add_i32 s14, s14, 1
	s_cmp_ge_u32 s12, s13
	s_cbranch_scc1 .Lmy_e1x4
	v_lshlrev_b32_e32 v38, 16, v208
	v_and_b32_e32 v39, 0xffff0000, v208
	v_lshlrev_b32_e32 v36, 16, v209
	v_and_b32_e32 v37, 0xffff0000, v209
	v_pk_add_f32 v[108:109], v[108:109], v[36:37]
	v_pk_add_f32 v[106:107], v[106:107], v[38:39]
	s_add_i32 s12, s12, 1
	s_add_i32 s14, s14, 1
	s_cmp_ge_u32 s12, s13
	s_cbranch_scc1 .Lmy_e1x4
	v_lshlrev_b32_e32 v38, 16, v210
	v_and_b32_e32 v39, 0xffff0000, v210
	v_lshlrev_b32_e32 v36, 16, v211
	v_and_b32_e32 v37, 0xffff0000, v211
	v_pk_add_f32 v[108:109], v[108:109], v[36:37]
	v_pk_add_f32 v[106:107], v[106:107], v[38:39]
	s_add_i32 s12, s12, 1
	s_add_i32 s14, s14, 1
	s_cmp_ge_u32 s12, s13
	s_cbranch_scc1 .Lmy_e1x4
	v_lshlrev_b32_e32 v38, 16, v212
	v_and_b32_e32 v39, 0xffff0000, v212
	v_lshlrev_b32_e32 v36, 16, v213
	v_and_b32_e32 v37, 0xffff0000, v213
	v_pk_add_f32 v[108:109], v[108:109], v[36:37]
	v_pk_add_f32 v[106:107], v[106:107], v[38:39]
	s_add_i32 s12, s12, 1
	s_add_i32 s14, s14, 1
	s_cmp_ge_u32 s12, s13
	s_cbranch_scc1 .Lmy_e1x4
	v_lshlrev_b32_e32 v38, 16, v214
	v_and_b32_e32 v39, 0xffff0000, v214
	v_lshlrev_b32_e32 v36, 16, v215
	v_and_b32_e32 v37, 0xffff0000, v215
	v_pk_add_f32 v[108:109], v[108:109], v[36:37]
	v_pk_add_f32 v[106:107], v[106:107], v[38:39]
	s_add_i32 s12, s12, 1
	s_add_i32 s14, s14, 1
	s_cmp_ge_u32 s12, s13
	s_cbranch_scc1 .Lmy_e1x4
	v_lshlrev_b32_e32 v38, 16, v216
	v_and_b32_e32 v39, 0xffff0000, v216
	v_lshlrev_b32_e32 v36, 16, v217
	v_and_b32_e32 v37, 0xffff0000, v217
	v_pk_add_f32 v[108:109], v[108:109], v[36:37]
	v_pk_add_f32 v[106:107], v[106:107], v[38:39]
	s_add_i32 s12, s12, 1
	s_add_i32 s14, s14, 1
	s_cmp_ge_u32 s12, s13
	s_cbranch_scc1 .Lmy_e1x4
	v_lshlrev_b32_e32 v38, 16, v218
	v_and_b32_e32 v39, 0xffff0000, v218
	v_lshlrev_b32_e32 v36, 16, v219
	v_and_b32_e32 v37, 0xffff0000, v219
	v_pk_add_f32 v[108:109], v[108:109], v[36:37]
	v_pk_add_f32 v[106:107], v[106:107], v[38:39]
	s_add_i32 s12, s12, 1
	s_add_i32 s14, s14, 1
	s_cmp_ge_u32 s12, s13
	s_cbranch_scc1 .Lmy_e1x4
	v_lshlrev_b32_e32 v38, 16, v220
	v_and_b32_e32 v39, 0xffff0000, v220
	v_lshlrev_b32_e32 v36, 16, v221
	v_and_b32_e32 v37, 0xffff0000, v221
	v_pk_add_f32 v[108:109], v[108:109], v[36:37]
	v_pk_add_f32 v[106:107], v[106:107], v[38:39]
	s_add_i32 s12, s12, 1
	s_add_i32 s14, s14, 1
	s_cmp_ge_u32 s12, s13
	s_cbranch_scc1 .Lmy_e1x4
	v_lshlrev_b32_e32 v38, 16, v222
	v_and_b32_e32 v39, 0xffff0000, v222
	v_lshlrev_b32_e32 v36, 16, v223
	v_and_b32_e32 v37, 0xffff0000, v223
	v_pk_add_f32 v[108:109], v[108:109], v[36:37]
	v_pk_add_f32 v[106:107], v[106:107], v[38:39]
	s_add_i32 s12, s12, 1
	s_add_i32 s14, s14, 1
	s_cmp_ge_u32 s12, s13
	s_cbranch_scc1 .Lmy_e1x4
	v_lshlrev_b32_e32 v38, 16, v224
	v_and_b32_e32 v39, 0xffff0000, v224
	v_lshlrev_b32_e32 v36, 16, v225
	v_and_b32_e32 v37, 0xffff0000, v225
	v_pk_add_f32 v[108:109], v[108:109], v[36:37]
	v_pk_add_f32 v[106:107], v[106:107], v[38:39]
	s_add_i32 s12, s12, 1
	s_add_i32 s14, s14, 1
	s_cmp_ge_u32 s12, s13
	s_cbranch_scc1 .Lmy_e1x4
	v_lshlrev_b32_e32 v38, 16, v226
	v_and_b32_e32 v39, 0xffff0000, v226
	v_lshlrev_b32_e32 v36, 16, v227
	v_and_b32_e32 v37, 0xffff0000, v227
	v_pk_add_f32 v[108:109], v[108:109], v[36:37]
	v_pk_add_f32 v[106:107], v[106:107], v[38:39]
	s_add_i32 s12, s12, 1
	s_add_i32 s14, s14, 1
	s_cmp_ge_u32 s12, s13
	s_cbranch_scc1 .Lmy_e1x4
	v_lshlrev_b32_e32 v38, 16, v228
	v_and_b32_e32 v39, 0xffff0000, v228
	v_lshlrev_b32_e32 v36, 16, v229
	v_and_b32_e32 v37, 0xffff0000, v229
	v_pk_add_f32 v[108:109], v[108:109], v[36:37]
	v_pk_add_f32 v[106:107], v[106:107], v[38:39]
	s_add_i32 s12, s12, 1
	s_add_i32 s14, s14, 1
	s_cmp_ge_u32 s12, s13
	s_cbranch_scc1 .Lmy_e1x4
	v_lshlrev_b32_e32 v38, 16, v230
	v_and_b32_e32 v39, 0xffff0000, v230
	v_lshlrev_b32_e32 v36, 16, v231
	v_and_b32_e32 v37, 0xffff0000, v231
	v_pk_add_f32 v[108:109], v[108:109], v[36:37]
	v_pk_add_f32 v[106:107], v[106:107], v[38:39]
	s_add_i32 s12, s12, 1
	s_add_i32 s14, s14, 1
	s_cmp_ge_u32 s12, s13
	s_cbranch_scc1 .Lmy_e1x4
	v_lshlrev_b32_e32 v38, 16, v232
	v_and_b32_e32 v39, 0xffff0000, v232
	v_lshlrev_b32_e32 v36, 16, v233
	v_and_b32_e32 v37, 0xffff0000, v233
	v_pk_add_f32 v[108:109], v[108:109], v[36:37]
	v_pk_add_f32 v[106:107], v[106:107], v[38:39]
	s_add_i32 s12, s12, 1
	s_add_i32 s14, s14, 1
	s_cmp_ge_u32 s12, s13
	s_cbranch_scc1 .Lmy_e1x4
	v_lshlrev_b32_e32 v38, 16, v234
	v_and_b32_e32 v39, 0xffff0000, v234
	v_lshlrev_b32_e32 v36, 16, v235
	v_and_b32_e32 v37, 0xffff0000, v235
	v_pk_add_f32 v[108:109], v[108:109], v[36:37]
	v_pk_add_f32 v[106:107], v[106:107], v[38:39]
	s_add_i32 s12, s12, 1
	s_add_i32 s14, s14, 1
	s_cmp_ge_u32 s12, s13
	s_cbranch_scc1 .Lmy_e1x4
	v_lshlrev_b32_e32 v38, 16, v236
	v_and_b32_e32 v39, 0xffff0000, v236
	v_lshlrev_b32_e32 v36, 16, v237
	v_and_b32_e32 v37, 0xffff0000, v237
	v_pk_add_f32 v[108:109], v[108:109], v[36:37]
	v_pk_add_f32 v[106:107], v[106:107], v[38:39]
	s_add_i32 s12, s12, 1
	s_add_i32 s14, s14, 1
	s_cmp_ge_u32 s12, s13
	s_cbranch_scc0 .LBB0_673
	s_branch .Lmy_e1x4
.LBB0_673:
	v_mad_i64_i32 v[36:37], s[24:25], s14, v34, v[32:33]
	global_load_dwordx2 v[36:37], v[36:37], off
	s_add_i32 s12, s12, 1
	s_add_i32 s14, s14, 1
	s_cmp_ge_u32 s12, s13
	s_waitcnt vmcnt(0)
	v_lshlrev_b32_e32 v38, 16, v36
	v_and_b32_e32 v39, 0xffff0000, v36
	v_lshlrev_b32_e32 v36, 16, v37
	v_and_b32_e32 v37, 0xffff0000, v37
	v_pk_add_f32 v[108:109], v[108:109], v[36:37]
	v_pk_add_f32 v[106:107], v[106:107], v[38:39]
	s_cbranch_scc0 .LBB0_673
.Lmy_e1x4:
	s_branch .LBB0_675
.LBB0_674:
	v_mov_b32_e32 v106, 0
	v_mov_b32_e32 v107, v106
	v_mov_b32_e32 v108, v106
	v_mov_b32_e32 v109, v106
